# v59 plus diff-attention item epilogue: sixteen 8-byte row stores widened to eight 16-byte stores via v_permlane32_swap pairs (docs 7.3)
# speedup vs baseline: 1.0108x; 1.0024x over previous
; __device__ __forceinline__ int diff_item(ldsp lds, int qt, int bh, bool pre, unsigned* nctr, const bf16* U, bf16* O, const float* subw, float lam, float omlinit, float M0, int wave, int lane) {
;     ...
;     if (c == 0) { const float inv = 1.0f / l; float ssq = 0.f;
; #pragma unroll
;         for (int et = 0; et < 4; ++et)
; #pragma unroll
;             for (int i = 0; i < 16; ++i) { const float d = o[et][i] * inv - xp[(et * 16 + i) * 64 + lane_e]; o[et][i] = d; ssq += d * d; }
;         ssq += shx(ssq, 32);
;         const float rs = omlinit / sqrtf(ssq * (1.0f / 128.0f) + EPS);
.LBB0_822:
	s_waitcnt lgkmcnt(0)
	s_barrier
	s_andn2_b64 vcc, exec, s[36:37]
	s_cbranch_vccnz .LBB0_804
	v_div_scale_f32 v2, s[14:15], v1, v1, 1.0
	v_rcp_f32_e32 v3, v2
	s_nop 0
	v_fma_f32 v4, -v2, v3, 1.0
	v_fmac_f32_e32 v3, v4, v3
	v_div_scale_f32 v4, vcc, 1.0, v1, 1.0
	v_mul_f32_e32 v5, v4, v3
	v_fma_f32 v6, -v2, v5, v4
	v_fmac_f32_e32 v5, v6, v3
	v_fma_f32 v2, -v2, v5, v4
	v_div_fmas_f32 v2, v2, v3, v5
	v_div_fixup_f32 v14, v2, v1, 1.0
	v_lshl_add_u32 v1, v0, 2, s96
	s_nop 0
	ds_read2st64_b32 v[134:135], v1 offset1:1
	ds_read2st64_b32 v[136:137], v1 offset0:2 offset1:3
	ds_read2st64_b32 v[138:139], v1 offset0:4 offset1:5
	ds_read2st64_b32 v[140:141], v1 offset0:6 offset1:7
	ds_read2st64_b32 v[62:63], v1 offset0:8 offset1:9
	ds_read2st64_b32 v[142:143], v1 offset0:10 offset1:11
	ds_read2st64_b32 v[54:55], v1 offset0:12 offset1:13
	ds_read2st64_b32 v[132:133], v1 offset0:14 offset1:15
	ds_read2st64_b32 v[48:49], v1 offset0:16 offset1:17
	ds_read2st64_b32 v[60:61], v1 offset0:18 offset1:19
	ds_read2st64_b32 v[44:45], v1 offset0:20 offset1:21
	ds_read2st64_b32 v[52:53], v1 offset0:22 offset1:23
	ds_read2st64_b32 v[42:43], v1 offset0:24 offset1:25
	ds_read2st64_b32 v[50:51], v1 offset0:26 offset1:27
	ds_read2st64_b32 v[36:37], v1 offset0:28 offset1:29
	ds_read2st64_b32 v[46:47], v1 offset0:30 offset1:31
	ds_read2st64_b32 v[30:31], v1 offset0:32 offset1:33
	ds_read2st64_b32 v[40:41], v1 offset0:34 offset1:35
	ds_read2st64_b32 v[26:27], v1 offset0:36 offset1:37
	ds_read2st64_b32 v[34:35], v1 offset0:38 offset1:39
	ds_read2st64_b32 v[24:25], v1 offset0:40 offset1:41
	ds_read2st64_b32 v[32:33], v1 offset0:42 offset1:43
	ds_read2st64_b32 v[28:29], v1 offset0:44 offset1:45
	s_nop 0
	ds_read2st64_b32 v[128:129], v1 offset0:46 offset1:47
	ds_read2st64_b32 v[22:23], v1 offset0:48 offset1:49
	ds_read2st64_b32 v[20:21], v1 offset0:50 offset1:51
	ds_read2st64_b32 v[18:19], v1 offset0:52 offset1:53
	ds_read2st64_b32 v[16:17], v1 offset0:54 offset1:55
	ds_read2st64_b32 v[56:57], v1 offset0:56 offset1:57
	ds_read2st64_b32 v[2:3], v1 offset0:58 offset1:59
	s_waitcnt lgkmcnt(14)
	v_pk_fma_f32 v[116:117], v[116:117], v[14:15], v[138:139] op_sel_hi:[1,0,1] neg_lo:[0,0,1] neg_hi:[0,0,1]
	s_waitcnt lgkmcnt(7)
	v_pk_fma_f32 v[28:29], v[92:93], v[14:15], v[28:29] op_sel_hi:[1,0,1] neg_lo:[0,0,1] neg_hi:[0,0,1]
	s_waitcnt lgkmcnt(4)
	v_pk_fma_f32 v[20:21], v[66:67], v[14:15], v[20:21] op_sel_hi:[1,0,1] neg_lo:[0,0,1] neg_hi:[0,0,1]
	v_pk_fma_f32 v[22:23], v[64:65], v[14:15], v[22:23] op_sel_hi:[1,0,1] neg_lo:[0,0,1] neg_hi:[0,0,1]
	s_waitcnt lgkmcnt(0)
	v_pk_fma_f32 v[4:5], v[74:75], v[14:15], v[2:3] op_sel_hi:[1,0,1] neg_lo:[0,0,1] neg_hi:[0,0,1]
	ds_read2st64_b32 v[2:3], v1 offset0:60 offset1:61
	v_pk_fma_f32 v[74:75], v[122:123], v[14:15], v[142:143] op_sel_hi:[1,0,1] neg_lo:[0,0,1] neg_hi:[0,0,1]
	v_pk_fma_f32 v[16:17], v[70:71], v[14:15], v[16:17] op_sel_hi:[1,0,1] neg_lo:[0,0,1] neg_hi:[0,0,1]
	v_pk_fma_f32 v[18:19], v[68:69], v[14:15], v[18:19] op_sel_hi:[1,0,1] neg_lo:[0,0,1] neg_hi:[0,0,1]
	v_pk_mul_f32 v[138:139], v[116:117], v[116:117]
	s_waitcnt lgkmcnt(0)
	v_pk_fma_f32 v[6:7], v[76:77], v[14:15], v[2:3] op_sel_hi:[1,0,1] neg_lo:[0,0,1] neg_hi:[0,0,1]
	ds_read2st64_b32 v[2:3], v1 offset0:62 offset1:63
	v_pk_fma_f32 v[76:77], v[124:125], v[14:15], v[54:55] op_sel_hi:[1,0,1] neg_lo:[0,0,1] neg_hi:[0,0,1]
	v_pk_fma_f32 v[54:55], v[98:99], v[14:15], v[60:61] op_sel_hi:[1,0,1] neg_lo:[0,0,1] neg_hi:[0,0,1]
	v_pk_fma_f32 v[60:61], v[96:97], v[14:15], v[48:49] op_sel_hi:[1,0,1] neg_lo:[0,0,1] neg_hi:[0,0,1]
	v_pk_fma_f32 v[48:49], v[102:103], v[14:15], v[52:53] op_sel_hi:[1,0,1] neg_lo:[0,0,1] neg_hi:[0,0,1]
	s_waitcnt lgkmcnt(0)
	v_pk_fma_f32 v[8:9], v[78:79], v[14:15], v[2:3] op_sel_hi:[1,0,1] neg_lo:[0,0,1] neg_hi:[0,0,1]
	v_pk_fma_f32 v[78:79], v[114:115], v[14:15], v[136:137] op_sel_hi:[1,0,1] neg_lo:[0,0,1] neg_hi:[0,0,1]
	v_pk_fma_f32 v[114:115], v[112:113], v[14:15], v[134:135] op_sel_hi:[1,0,1] neg_lo:[0,0,1] neg_hi:[0,0,1]
	v_pk_mul_f32 v[136:137], v[78:79], v[78:79]
	v_pk_mul_f32 v[134:135], v[114:115], v[114:115]
	v_pk_fma_f32 v[112:113], v[118:119], v[14:15], v[140:141] op_sel_hi:[1,0,1] neg_lo:[0,0,1] neg_hi:[0,0,1]
	v_pk_fma_f32 v[118:119], v[120:121], v[14:15], v[62:63] op_sel_hi:[1,0,1] neg_lo:[0,0,1] neg_hi:[0,0,1]
	v_pk_fma_f32 v[62:63], v[126:127], v[14:15], v[132:133] op_sel_hi:[1,0,1] neg_lo:[0,0,1] neg_hi:[0,0,1]
	v_pk_fma_f32 v[52:53], v[100:101], v[14:15], v[44:45] op_sel_hi:[1,0,1] neg_lo:[0,0,1] neg_hi:[0,0,1]
	v_pk_fma_f32 v[44:45], v[106:107], v[14:15], v[50:51] op_sel_hi:[1,0,1] neg_lo:[0,0,1] neg_hi:[0,0,1]
	v_pk_fma_f32 v[50:51], v[104:105], v[14:15], v[42:43] op_sel_hi:[1,0,1] neg_lo:[0,0,1] neg_hi:[0,0,1]
	v_pk_fma_f32 v[42:43], v[110:111], v[14:15], v[46:47] op_sel_hi:[1,0,1] neg_lo:[0,0,1] neg_hi:[0,0,1]
	v_pk_fma_f32 v[46:47], v[108:109], v[14:15], v[36:37] op_sel_hi:[1,0,1] neg_lo:[0,0,1] neg_hi:[0,0,1]
	v_pk_fma_f32 v[36:37], v[82:83], v[14:15], v[40:41] op_sel_hi:[1,0,1] neg_lo:[0,0,1] neg_hi:[0,0,1]
	v_pk_fma_f32 v[40:41], v[80:81], v[14:15], v[30:31] op_sel_hi:[1,0,1] neg_lo:[0,0,1] neg_hi:[0,0,1]
	v_pk_fma_f32 v[30:31], v[86:87], v[14:15], v[34:35] op_sel_hi:[1,0,1] neg_lo:[0,0,1] neg_hi:[0,0,1]
	v_pk_fma_f32 v[34:35], v[84:85], v[14:15], v[26:27] op_sel_hi:[1,0,1] neg_lo:[0,0,1] neg_hi:[0,0,1]
	v_pk_fma_f32 v[26:27], v[90:91], v[14:15], v[32:33] op_sel_hi:[1,0,1] neg_lo:[0,0,1] neg_hi:[0,0,1]
	v_pk_fma_f32 v[32:33], v[88:89], v[14:15], v[24:25] op_sel_hi:[1,0,1] neg_lo:[0,0,1] neg_hi:[0,0,1]
	v_pk_fma_f32 v[24:25], v[94:95], v[14:15], v[128:129] op_sel_hi:[1,0,1] neg_lo:[0,0,1] neg_hi:[0,0,1]
	v_pk_fma_f32 v[14:15], v[72:73], v[14:15], v[56:57] op_sel_hi:[1,0,1] neg_lo:[0,0,1] neg_hi:[0,0,1]
	v_add_f32_e32 v72, v134, v135
	v_add_f32_e32 v72, v72, v136
	v_add_f32_e32 v72, v72, v137
	v_add_f32_e32 v72, v72, v138
	v_pk_mul_f32 v[140:141], v[112:113], v[112:113]
	v_add_f32_e32 v72, v72, v139
	v_add_f32_e32 v72, v72, v140
	v_pk_mul_f32 v[120:121], v[118:119], v[118:119]
	v_add_f32_e32 v72, v72, v141
	v_add_f32_e32 v72, v72, v120
	v_pk_mul_f32 v[122:123], v[74:75], v[74:75]
	v_add_f32_e32 v72, v72, v121
	v_add_f32_e32 v72, v72, v122
	v_pk_mul_f32 v[124:125], v[76:77], v[76:77]
	v_add_f32_e32 v72, v72, v123
	v_add_f32_e32 v72, v72, v124
	v_pk_mul_f32 v[126:127], v[62:63], v[62:63]
	v_add_f32_e32 v72, v72, v125
	v_add_f32_e32 v72, v72, v126
	v_mov_b32_e32 v1, v201
	v_and_or_b32 v2, v0, 31, s76
	v_mov_b32_e32 v3, s77
	v_pk_mul_f32 v[96:97], v[60:61], v[60:61]
	v_add_f32_e32 v72, v72, v127
	v_lshlrev_b64 v[2:3], 11, v[2:3]
	v_ashrrev_i32_e32 v0, 3, v0
	v_add_f32_e32 v72, v72, v96
	v_lshlrev_b32_e32 v1, 2, v1
	v_lshl_add_u64 v[2:3], s[22:23], 0, v[2:3]
	v_and_b32_e32 v0, -4, v0
	v_pk_mul_f32 v[98:99], v[54:55], v[54:55]
	v_add_f32_e32 v72, v72, v97
	v_xor_b32_e32 v144, 0x80, v1
	v_lshl_add_u64 v[2:3], s[10:11], 1, v[2:3]
	v_ashrrev_i32_e32 v1, 31, v0
	s_load_dwordx2 s[10:11], s[46:47], 0x80
	v_add_f32_e32 v72, v72, v98
	s_waitcnt lgkmcnt(0)
; __device__ __forceinline__ unsigned cvtpk(float lo, float hi) { f32x2_t v = {lo, hi}; bf16x2_t b = __builtin_convertvector(v, bf16x2_t); return __builtin_bit_cast(unsigned, b); }
; __device__ __forceinline__ int diff_item(ldsp lds, int qt, int bh, bool pre, unsigned* nctr, const bf16* U, bf16* O, const float* subw, float lam, float omlinit, float M0, int wave, int lane) {
;     ...
;             for (int i = 0; i < 16; ++i) { const float d = o[et][i] * inv - xp[(et * 16 + i) * 64 + lane_e]; o[et][i] = d; ssq += d * d; }
;         ssq += shx(ssq, 32);
;         const float rs = omlinit / sqrtf(ssq * (1.0f / 128.0f) + EPS);
;         bf16* op = O + (tokbase + t0 + r_e) * D + h * 128 + 4 * hh_e;
;         const float* swp = subw; asm volatile("" : "+s"(swp));
; #pragma unroll
;         for (int et = 0; et < 4; ++et)
; #pragma unroll
;             for (int g4 = 0; g4 < 4; ++g4) { const int e0 = 32 * et + 8 * g4; const f32x4 w = *(const f32x4*)(swp + e0 + 4 * hh_e);
;                 v2u pk; pk.x = cvtpk(o[et][4 * g4] * rs * w[0], o[et][4 * g4 + 1] * rs * w[1]); pk.y = cvtpk(o[et][4 * g4 + 2] * rs * w[2], o[et][4 * g4 + 3] * rs * w[3]);
;                 *(v2u*)(op + e0) = pk; }
	v_pk_mul_f32 v[100:101], v[52:53], v[52:53]
	v_lshlrev_b32_e32 v12, 2, v0
	v_add_u32_e32 v12, 0x20080, v12
	v_add_f32_e32 v72, v72, v99
	v_lshl_add_u64 v[10:11], v[0:1], 1, v[2:3]
	v_and_b32_e32 v146, 32, v152
	v_lshrrev_b32_e32 v146, 2, v146
	v_mov_b32_e32 v147, 0
	v_lshl_add_u64 v[10:11], v[10:11], 0, v[146:147]
	ds_read_b128 v[0:3], v12
	v_add_f32_e32 v72, v72, v100
	v_pk_mul_f32 v[102:103], v[48:49], v[48:49]
	v_add_f32_e32 v72, v72, v101
	v_add_f32_e32 v72, v72, v102
	v_pk_mul_f32 v[104:105], v[50:51], v[50:51]
	v_add_f32_e32 v72, v72, v103
	v_add_f32_e32 v72, v72, v104
	v_pk_mul_f32 v[106:107], v[44:45], v[44:45]
	v_add_f32_e32 v72, v72, v105
	v_add_f32_e32 v72, v72, v106
	v_pk_mul_f32 v[108:109], v[46:47], v[46:47]
	v_add_f32_e32 v72, v72, v107
	v_add_f32_e32 v72, v72, v108
	v_pk_mul_f32 v[110:111], v[42:43], v[42:43]
	v_add_f32_e32 v72, v72, v109
	v_add_f32_e32 v72, v72, v110
	v_pk_mul_f32 v[80:81], v[40:41], v[40:41]
	v_add_f32_e32 v72, v72, v111
	v_add_f32_e32 v72, v72, v80
	v_pk_mul_f32 v[82:83], v[36:37], v[36:37]
	v_add_f32_e32 v72, v72, v81
	v_add_f32_e32 v72, v72, v82
	v_pk_mul_f32 v[84:85], v[34:35], v[34:35]
	v_add_f32_e32 v72, v72, v83
	v_add_f32_e32 v72, v72, v84
	v_pk_mul_f32 v[86:87], v[30:31], v[30:31]
	v_add_f32_e32 v72, v72, v85
	v_add_f32_e32 v72, v72, v86
	v_pk_mul_f32 v[88:89], v[32:33], v[32:33]
	v_add_f32_e32 v72, v72, v87
	v_add_f32_e32 v72, v72, v88
	v_pk_mul_f32 v[90:91], v[26:27], v[26:27]
	v_add_f32_e32 v72, v72, v89
	v_add_f32_e32 v72, v72, v90
	v_pk_mul_f32 v[92:93], v[28:29], v[28:29]
	v_add_f32_e32 v72, v72, v91
	v_add_f32_e32 v72, v72, v92
	v_pk_mul_f32 v[94:95], v[24:25], v[24:25]
	v_add_f32_e32 v72, v72, v93
	v_add_f32_e32 v72, v72, v94
	v_pk_mul_f32 v[64:65], v[22:23], v[22:23]
	v_add_f32_e32 v72, v72, v95
	v_add_f32_e32 v64, v72, v64
	v_pk_mul_f32 v[66:67], v[20:21], v[20:21]
	v_add_f32_e32 v64, v64, v65
	v_add_f32_e32 v64, v64, v66
	v_pk_mul_f32 v[68:69], v[18:19], v[18:19]
	v_add_f32_e32 v64, v64, v67
	v_add_f32_e32 v64, v64, v68
	v_pk_mul_f32 v[70:71], v[16:17], v[16:17]
	v_add_f32_e32 v64, v64, v69
	v_add_f32_e32 v64, v64, v70
	v_pk_mul_f32 v[56:57], v[14:15], v[14:15]
	v_add_f32_e32 v64, v64, v71
	v_add_f32_e32 v56, v64, v56
	v_pk_mul_f32 v[38:39], v[4:5], v[4:5]
	v_add_f32_e32 v56, v56, v57
	v_add_f32_e32 v38, v56, v38
	v_pk_mul_f32 v[58:59], v[6:7], v[6:7]
	v_add_f32_e32 v38, v38, v39
	v_add_f32_e32 v38, v38, v58
	v_pk_mul_f32 v[130:131], v[8:9], v[8:9]
	v_add_f32_e32 v38, v38, v59
	v_add_f32_e32 v38, v38, v130
	v_add_f32_e32 v38, v38, v131
	ds_bpermute_b32 v39, v144, v38
	s_mov_b32 s10, 0xf800000
	s_waitcnt lgkmcnt(0)
	v_add_f32_e32 v38, v38, v39
	v_fmamk_f32 v38, v38, 0x3c000000, v209
	v_cmp_gt_f32_e32 vcc, s10, v38
	v_mul_f32_e32 v39, 0x4f800000, v38
	s_nop 0
	v_cndmask_b32_e32 v38, v38, v39, vcc
	v_sqrt_f32_e32 v39, v38
	s_nop 0
	v_add_u32_e32 v56, -1, v39
	v_fma_f32 v57, -v56, v39, v38
	v_cmp_ge_f32_e64 s[10:11], 0, v57
	v_add_u32_e32 v57, 1, v39
	s_nop 0
	v_cndmask_b32_e64 v56, v39, v56, s[10:11]
	v_fma_f32 v39, -v57, v39, v38
	v_cmp_lt_f32_e64 s[10:11], 0, v39
	s_nop 1
	v_cndmask_b32_e64 v39, v56, v57, s[10:11]
	v_mul_f32_e32 v56, 0x37800000, v39
	v_cndmask_b32_e32 v39, v39, v56, vcc
	v_cmp_class_f32_e32 vcc, v38, v210
	s_nop 1
	v_cndmask_b32_e32 v38, v39, v38, vcc
	v_div_scale_f32 v39, s[10:11], v38, v38, s33
	v_rcp_f32_e32 v56, v39
	s_nop 0
	v_fma_f32 v57, -v39, v56, 1.0
	v_fmac_f32_e32 v56, v57, v56
	v_div_scale_f32 v57, vcc, s33, v38, s33
	v_mul_f32_e32 v58, v57, v56
	v_fma_f32 v59, -v39, v58, v57
	v_fmac_f32_e32 v58, v59, v56
	v_fma_f32 v39, -v39, v58, v57
	v_div_fmas_f32 v39, v39, v56, v58
	v_div_fixup_f32 v38, v39, v38, s33
	v_pk_mul_f32 v[56:57], v[114:115], v[38:39] op_sel_hi:[1,0]
	v_pk_mul_f32 v[54:55], v[54:55], v[38:39] op_sel_hi:[1,0]
	s_waitcnt lgkmcnt(0)
	v_pk_mul_f32 v[0:1], v[0:1], v[56:57]
	v_pk_mul_f32 v[56:57], v[78:79], v[38:39] op_sel_hi:[1,0]
	v_cvt_pk_bf16_f32 v0, v0, v1
	v_pk_mul_f32 v[2:3], v[2:3], v[56:57]
	v_pk_mul_f32 v[56:57], v[116:117], v[38:39] op_sel_hi:[1,0]
	v_cvt_pk_bf16_f32 v1, v2, v3
	ds_read_b128 v[148:151], v12 offset:32
	v_pk_mul_f32 v[52:53], v[52:53], v[38:39] op_sel_hi:[1,0]
	v_pk_mul_f32 v[48:49], v[48:49], v[38:39] op_sel_hi:[1,0]
	v_pk_mul_f32 v[44:45], v[44:45], v[38:39] op_sel_hi:[1,0]
	v_pk_mul_f32 v[42:43], v[42:43], v[38:39] op_sel_hi:[1,0]
	v_pk_mul_f32 v[40:41], v[40:41], v[38:39] op_sel_hi:[1,0]
	v_pk_mul_f32 v[36:37], v[36:37], v[38:39] op_sel_hi:[1,0]
	v_pk_mul_f32 v[34:35], v[34:35], v[38:39] op_sel_hi:[1,0]
	v_pk_mul_f32 v[30:31], v[30:31], v[38:39] op_sel_hi:[1,0]
	v_pk_mul_f32 v[26:27], v[26:27], v[38:39] op_sel_hi:[1,0]
	v_pk_mul_f32 v[24:25], v[24:25], v[38:39] op_sel_hi:[1,0]
	v_pk_mul_f32 v[22:23], v[22:23], v[38:39] op_sel_hi:[1,0]
	v_pk_mul_f32 v[20:21], v[20:21], v[38:39] op_sel_hi:[1,0]
	v_pk_mul_f32 v[18:19], v[18:19], v[38:39] op_sel_hi:[1,0]
	v_pk_mul_f32 v[16:17], v[16:17], v[38:39] op_sel_hi:[1,0]
	v_pk_mul_f32 v[14:15], v[14:15], v[38:39] op_sel_hi:[1,0]
	v_pk_mul_f32 v[4:5], v[4:5], v[38:39] op_sel_hi:[1,0]
	s_waitcnt lgkmcnt(0)
; __device__ __forceinline__ unsigned cvtpk(float lo, float hi) { f32x2_t v = {lo, hi}; bf16x2_t b = __builtin_convertvector(v, bf16x2_t); return __builtin_bit_cast(unsigned, b); }
; __device__ __forceinline__ int diff_item(ldsp lds, int qt, int bh, bool pre, unsigned* nctr, const bf16* U, bf16* O, const float* subw, float lam, float omlinit, float M0, int wave, int lane) {
;     ...
;         for (int et = 0; et < 4; ++et)
; #pragma unroll
;             for (int g4 = 0; g4 < 4; ++g4) { const int e0 = 32 * et + 8 * g4; const f32x4 w = *(const f32x4*)(swp + e0 + 4 * hh_e);
;                 v2u pk; pk.x = cvtpk(o[et][4 * g4] * rs * w[0], o[et][4 * g4 + 1] * rs * w[1]); pk.y = cvtpk(o[et][4 * g4 + 2] * rs * w[2], o[et][4 * g4 + 3] * rs * w[3]);
;                 *(v2u*)(op + e0) = pk; }
	v_pk_mul_f32 v[148:149], v[148:149], v[56:57]
	v_pk_mul_f32 v[56:57], v[112:113], v[38:39] op_sel_hi:[1,0]
	v_cvt_pk_bf16_f32 v2, v148, v149
	v_pk_mul_f32 v[150:151], v[150:151], v[56:57]
	v_pk_mul_f32 v[56:57], v[118:119], v[38:39] op_sel_hi:[1,0]
	v_cvt_pk_bf16_f32 v3, v150, v151
	s_nop 1
	v_permlane32_swap_b32_e32 v0, v2
	v_permlane32_swap_b32_e32 v1, v3
	global_store_dwordx4 v[10:11], v[0:3], off
	s_nop 1
	ds_read_b128 v[0:3], v12 offset:64
	s_waitcnt lgkmcnt(0)
	v_pk_mul_f32 v[0:1], v[0:1], v[56:57]
	v_pk_mul_f32 v[56:57], v[74:75], v[38:39] op_sel_hi:[1,0]
	v_cvt_pk_bf16_f32 v0, v0, v1
	v_pk_mul_f32 v[2:3], v[2:3], v[56:57]
	v_pk_mul_f32 v[56:57], v[76:77], v[38:39] op_sel_hi:[1,0]
	v_cvt_pk_bf16_f32 v1, v2, v3
	ds_read_b128 v[148:151], v12 offset:96
	s_waitcnt lgkmcnt(0)
	v_pk_mul_f32 v[148:149], v[56:57], v[148:149]
	v_pk_mul_f32 v[56:57], v[62:63], v[38:39] op_sel_hi:[1,0]
	v_cvt_pk_bf16_f32 v2, v148, v149
	v_pk_mul_f32 v[150:151], v[56:57], v[150:151]
	v_pk_mul_f32 v[56:57], v[60:61], v[38:39] op_sel_hi:[1,0]
	v_cvt_pk_bf16_f32 v3, v150, v151
	s_nop 1
	v_permlane32_swap_b32_e32 v0, v2
	v_permlane32_swap_b32_e32 v1, v3
	global_store_dwordx4 v[10:11], v[0:3], off offset:32
	s_nop 1
	ds_read_b128 v[0:3], v12 offset:128
	s_waitcnt lgkmcnt(0)
	v_pk_mul_f32 v[0:1], v[56:57], v[0:1]
	v_pk_mul_f32 v[2:3], v[54:55], v[2:3]
	v_cvt_pk_bf16_f32 v0, v0, v1
	v_cvt_pk_bf16_f32 v1, v2, v3
	ds_read_b128 v[148:151], v12 offset:160
	s_waitcnt lgkmcnt(0)
	v_pk_mul_f32 v[148:149], v[52:53], v[148:149]
	v_pk_mul_f32 v[150:151], v[48:49], v[150:151]
	v_cvt_pk_bf16_f32 v2, v148, v149
	v_cvt_pk_bf16_f32 v3, v150, v151
	s_nop 1
	v_permlane32_swap_b32_e32 v0, v2
	v_permlane32_swap_b32_e32 v1, v3
	global_store_dwordx4 v[10:11], v[0:3], off offset:64
	s_nop 1
	ds_read_b128 v[0:3], v12 offset:192
	v_pk_mul_f32 v[48:49], v[50:51], v[38:39] op_sel_hi:[1,0]
	s_waitcnt lgkmcnt(0)
	v_pk_mul_f32 v[2:3], v[44:45], v[2:3]
	v_pk_mul_f32 v[0:1], v[48:49], v[0:1]
	v_pk_mul_f32 v[44:45], v[46:47], v[38:39] op_sel_hi:[1,0]
	v_cvt_pk_bf16_f32 v0, v0, v1
	v_cvt_pk_bf16_f32 v1, v2, v3
	ds_read_b128 v[148:151], v12 offset:224
	s_waitcnt lgkmcnt(0)
	v_pk_mul_f32 v[148:149], v[44:45], v[148:149]
	v_pk_mul_f32 v[150:151], v[42:43], v[150:151]
	v_cvt_pk_bf16_f32 v2, v148, v149
	v_cvt_pk_bf16_f32 v3, v150, v151
	s_nop 1
	v_permlane32_swap_b32_e32 v0, v2
	v_permlane32_swap_b32_e32 v1, v3
	global_store_dwordx4 v[10:11], v[0:3], off offset:96
	s_nop 1
	ds_read_b128 v[0:3], v12 offset:256
	s_waitcnt lgkmcnt(0)
	v_pk_mul_f32 v[0:1], v[40:41], v[0:1]
	v_pk_mul_f32 v[2:3], v[36:37], v[2:3]
	v_cvt_pk_bf16_f32 v0, v0, v1
	v_cvt_pk_bf16_f32 v1, v2, v3
	ds_read_b128 v[148:151], v12 offset:288
	s_waitcnt lgkmcnt(0)
	v_pk_mul_f32 v[148:149], v[34:35], v[148:149]
	v_pk_mul_f32 v[150:151], v[30:31], v[150:151]
	v_cvt_pk_bf16_f32 v2, v148, v149
	v_cvt_pk_bf16_f32 v3, v150, v151
	s_nop 1
	v_permlane32_swap_b32_e32 v0, v2
	v_permlane32_swap_b32_e32 v1, v3
	global_store_dwordx4 v[10:11], v[0:3], off offset:128
	s_nop 1
	ds_read_b128 v[0:3], v12 offset:320
	v_pk_mul_f32 v[30:31], v[32:33], v[38:39] op_sel_hi:[1,0]
	s_waitcnt lgkmcnt(0)
	v_pk_mul_f32 v[2:3], v[26:27], v[2:3]
	v_pk_mul_f32 v[0:1], v[30:31], v[0:1]
	v_pk_mul_f32 v[26:27], v[28:29], v[38:39] op_sel_hi:[1,0]
	v_cvt_pk_bf16_f32 v0, v0, v1
	v_cvt_pk_bf16_f32 v1, v2, v3
	ds_read_b128 v[148:151], v12 offset:352
	s_waitcnt lgkmcnt(0)
	v_pk_mul_f32 v[148:149], v[26:27], v[148:149]
	v_pk_mul_f32 v[150:151], v[24:25], v[150:151]
	v_cvt_pk_bf16_f32 v2, v148, v149
	v_cvt_pk_bf16_f32 v3, v150, v151
	s_nop 1
	v_permlane32_swap_b32_e32 v0, v2
	v_permlane32_swap_b32_e32 v1, v3
	global_store_dwordx4 v[10:11], v[0:3], off offset:160
	s_nop 1
	ds_read_b128 v[0:3], v12 offset:384
	s_waitcnt lgkmcnt(0)
	v_pk_mul_f32 v[0:1], v[22:23], v[0:1]
	v_pk_mul_f32 v[2:3], v[20:21], v[2:3]
	v_cvt_pk_bf16_f32 v0, v0, v1
	v_cvt_pk_bf16_f32 v1, v2, v3
	ds_read_b128 v[148:151], v12 offset:416
	s_waitcnt lgkmcnt(0)
	v_pk_mul_f32 v[148:149], v[18:19], v[148:149]
	v_pk_mul_f32 v[150:151], v[16:17], v[150:151]
	v_cvt_pk_bf16_f32 v2, v148, v149
	v_cvt_pk_bf16_f32 v3, v150, v151
	s_nop 1
	v_permlane32_swap_b32_e32 v0, v2
	v_permlane32_swap_b32_e32 v1, v3
	global_store_dwordx4 v[10:11], v[0:3], off offset:192
	s_nop 1
	ds_read_b128 v[0:3], v12 offset:448
	s_waitcnt lgkmcnt(0)
	v_pk_mul_f32 v[0:1], v[14:15], v[0:1]
	v_pk_mul_f32 v[2:3], v[4:5], v[2:3]
	v_cvt_pk_bf16_f32 v0, v0, v1
	v_cvt_pk_bf16_f32 v1, v2, v3
	ds_read_b128 v[148:151], v12 offset:480
	v_pk_mul_f32 v[4:5], v[6:7], v[38:39] op_sel_hi:[1,0]
	s_waitcnt lgkmcnt(0)
	v_pk_mul_f32 v[148:149], v[4:5], v[148:149]
	v_pk_mul_f32 v[4:5], v[8:9], v[38:39] op_sel_hi:[1,0]
	v_cvt_pk_bf16_f32 v2, v148, v149
	v_pk_mul_f32 v[150:151], v[4:5], v[150:151]
	s_nop 0
	v_cvt_pk_bf16_f32 v3, v150, v151
	s_nop 1
	v_permlane32_swap_b32_e32 v0, v2
	v_permlane32_swap_b32_e32 v1, v3
	global_store_dwordx4 v[10:11], v[0:3], off offset:224
	s_nop 1
	s_branch .LBB0_804

; __device__ __forceinline__ int diff_item(ldsp lds, int qt, int bh, bool pre, unsigned* nctr, const bf16* U, bf16* O, const float* subw, float lam, float omlinit, float M0, int wave, int lane) {
;     ...
;     if (c == 0) { const float inv = 1.0f / l; float ssq = 0.f;
; #pragma unroll
;         for (int et = 0; et < 4; ++et)
; #pragma unroll
;             for (int i = 0; i < 16; ++i) { const float d = o[et][i] * inv - xp[(et * 16 + i) * 64 + lane_e]; o[et][i] = d; ssq += d * d; }
;         ssq += shx(ssq, 32);
;         const float rs = omlinit / sqrtf(ssq * (1.0f / 128.0f) + EPS);
.LBB0_1866:
	s_waitcnt lgkmcnt(0)
	s_barrier
	s_andn2_b64 vcc, exec, s[36:37]
	s_cbranch_vccnz .LBB0_1848
	v_div_scale_f32 v2, s[4:5], v1, v1, 1.0
	v_rcp_f32_e32 v3, v2
	s_mov_b64 s[4:5], s[24:25]
	v_fma_f32 v4, -v2, v3, 1.0
	v_fmac_f32_e32 v3, v4, v3
	v_div_scale_f32 v4, vcc, 1.0, v1, 1.0
	v_mul_f32_e32 v5, v4, v3
	v_fma_f32 v6, -v2, v5, v4
	v_fmac_f32_e32 v5, v6, v3
	v_fma_f32 v2, -v2, v5, v4
	v_div_fmas_f32 v2, v2, v3, v5
	v_div_fixup_f32 v14, v2, v1, 1.0
	v_lshl_add_u32 v1, v0, 2, s96
	ds_read2st64_b32 v[60:61], v1 offset1:1
	ds_read2st64_b32 v[62:63], v1 offset0:2 offset1:3
	s_nop 0
	ds_read2st64_b32 v[132:133], v1 offset0:4 offset1:5
	ds_read2st64_b32 v[134:135], v1 offset0:6 offset1:7
	ds_read2st64_b32 v[136:137], v1 offset0:8 offset1:9
	ds_read2st64_b32 v[138:139], v1 offset0:10 offset1:11
	ds_read2st64_b32 v[54:55], v1 offset0:12 offset1:13
	ds_read2st64_b32 v[140:141], v1 offset0:14 offset1:15
	ds_read2st64_b32 v[48:49], v1 offset0:16 offset1:17
	ds_read2st64_b32 v[142:143], v1 offset0:18 offset1:19
	ds_read2st64_b32 v[44:45], v1 offset0:20 offset1:21
	ds_read2st64_b32 v[52:53], v1 offset0:22 offset1:23
	ds_read2st64_b32 v[42:43], v1 offset0:24 offset1:25
	ds_read2st64_b32 v[50:51], v1 offset0:26 offset1:27
	ds_read2st64_b32 v[36:37], v1 offset0:28 offset1:29
	ds_read2st64_b32 v[46:47], v1 offset0:30 offset1:31
	ds_read2st64_b32 v[30:31], v1 offset0:32 offset1:33
	ds_read2st64_b32 v[40:41], v1 offset0:34 offset1:35
	ds_read2st64_b32 v[26:27], v1 offset0:36 offset1:37
	ds_read2st64_b32 v[34:35], v1 offset0:38 offset1:39
	ds_read2st64_b32 v[24:25], v1 offset0:40 offset1:41
	ds_read2st64_b32 v[32:33], v1 offset0:42 offset1:43
	ds_read2st64_b32 v[28:29], v1 offset0:44 offset1:45
	s_nop 0
	ds_read2st64_b32 v[128:129], v1 offset0:46 offset1:47
	ds_read2st64_b32 v[22:23], v1 offset0:48 offset1:49
	ds_read2st64_b32 v[20:21], v1 offset0:50 offset1:51
	ds_read2st64_b32 v[18:19], v1 offset0:52 offset1:53
	ds_read2st64_b32 v[16:17], v1 offset0:54 offset1:55
	ds_read2st64_b32 v[56:57], v1 offset0:56 offset1:57
	ds_read2st64_b32 v[2:3], v1 offset0:58 offset1:59
	s_waitcnt lgkmcnt(14)
	v_pk_fma_f32 v[116:117], v[116:117], v[14:15], v[132:133] op_sel_hi:[1,0,1] neg_lo:[0,0,1] neg_hi:[0,0,1]
	s_waitcnt lgkmcnt(7)
	v_pk_fma_f32 v[28:29], v[92:93], v[14:15], v[28:29] op_sel_hi:[1,0,1] neg_lo:[0,0,1] neg_hi:[0,0,1]
	s_waitcnt lgkmcnt(4)
	v_pk_fma_f32 v[20:21], v[66:67], v[14:15], v[20:21] op_sel_hi:[1,0,1] neg_lo:[0,0,1] neg_hi:[0,0,1]
	v_pk_fma_f32 v[22:23], v[64:65], v[14:15], v[22:23] op_sel_hi:[1,0,1] neg_lo:[0,0,1] neg_hi:[0,0,1]
	s_waitcnt lgkmcnt(0)
	v_pk_fma_f32 v[4:5], v[74:75], v[14:15], v[2:3] op_sel_hi:[1,0,1] neg_lo:[0,0,1] neg_hi:[0,0,1]
	ds_read2st64_b32 v[2:3], v1 offset0:60 offset1:61
	v_pk_fma_f32 v[74:75], v[122:123], v[14:15], v[138:139] op_sel_hi:[1,0,1] neg_lo:[0,0,1] neg_hi:[0,0,1]
	v_pk_fma_f32 v[16:17], v[70:71], v[14:15], v[16:17] op_sel_hi:[1,0,1] neg_lo:[0,0,1] neg_hi:[0,0,1]
	v_pk_fma_f32 v[18:19], v[68:69], v[14:15], v[18:19] op_sel_hi:[1,0,1] neg_lo:[0,0,1] neg_hi:[0,0,1]
	v_pk_mul_f32 v[132:133], v[116:117], v[116:117]
	s_waitcnt lgkmcnt(0)
	v_pk_fma_f32 v[6:7], v[76:77], v[14:15], v[2:3] op_sel_hi:[1,0,1] neg_lo:[0,0,1] neg_hi:[0,0,1]
	ds_read2st64_b32 v[2:3], v1 offset0:62 offset1:63
	v_pk_fma_f32 v[76:77], v[124:125], v[14:15], v[54:55] op_sel_hi:[1,0,1] neg_lo:[0,0,1] neg_hi:[0,0,1]
	v_pk_fma_f32 v[54:55], v[98:99], v[14:15], v[142:143] op_sel_hi:[1,0,1] neg_lo:[0,0,1] neg_hi:[0,0,1]
	v_pk_mul_f32 v[122:123], v[74:75], v[74:75]
	v_pk_mul_f32 v[124:125], v[76:77], v[76:77]
	s_waitcnt lgkmcnt(0)
	v_pk_fma_f32 v[8:9], v[78:79], v[14:15], v[2:3] op_sel_hi:[1,0,1] neg_lo:[0,0,1] neg_hi:[0,0,1]
	v_pk_fma_f32 v[78:79], v[114:115], v[14:15], v[62:63] op_sel_hi:[1,0,1] neg_lo:[0,0,1] neg_hi:[0,0,1]
	v_pk_fma_f32 v[114:115], v[112:113], v[14:15], v[60:61] op_sel_hi:[1,0,1] neg_lo:[0,0,1] neg_hi:[0,0,1]
	v_pk_mul_f32 v[144:145], v[78:79], v[78:79]
	v_pk_mul_f32 v[146:147], v[114:115], v[114:115]
	v_pk_fma_f32 v[112:113], v[118:119], v[14:15], v[134:135] op_sel_hi:[1,0,1] neg_lo:[0,0,1] neg_hi:[0,0,1]
	v_pk_fma_f32 v[118:119], v[120:121], v[14:15], v[136:137] op_sel_hi:[1,0,1] neg_lo:[0,0,1] neg_hi:[0,0,1]
	v_pk_fma_f32 v[62:63], v[126:127], v[14:15], v[140:141] op_sel_hi:[1,0,1] neg_lo:[0,0,1] neg_hi:[0,0,1]
	v_pk_fma_f32 v[60:61], v[96:97], v[14:15], v[48:49] op_sel_hi:[1,0,1] neg_lo:[0,0,1] neg_hi:[0,0,1]
	v_pk_fma_f32 v[48:49], v[102:103], v[14:15], v[52:53] op_sel_hi:[1,0,1] neg_lo:[0,0,1] neg_hi:[0,0,1]
	v_pk_fma_f32 v[52:53], v[100:101], v[14:15], v[44:45] op_sel_hi:[1,0,1] neg_lo:[0,0,1] neg_hi:[0,0,1]
	v_pk_fma_f32 v[44:45], v[106:107], v[14:15], v[50:51] op_sel_hi:[1,0,1] neg_lo:[0,0,1] neg_hi:[0,0,1]
	v_pk_fma_f32 v[50:51], v[104:105], v[14:15], v[42:43] op_sel_hi:[1,0,1] neg_lo:[0,0,1] neg_hi:[0,0,1]
	v_pk_fma_f32 v[42:43], v[110:111], v[14:15], v[46:47] op_sel_hi:[1,0,1] neg_lo:[0,0,1] neg_hi:[0,0,1]
	v_pk_fma_f32 v[46:47], v[108:109], v[14:15], v[36:37] op_sel_hi:[1,0,1] neg_lo:[0,0,1] neg_hi:[0,0,1]
	v_pk_fma_f32 v[36:37], v[82:83], v[14:15], v[40:41] op_sel_hi:[1,0,1] neg_lo:[0,0,1] neg_hi:[0,0,1]
	v_pk_fma_f32 v[40:41], v[80:81], v[14:15], v[30:31] op_sel_hi:[1,0,1] neg_lo:[0,0,1] neg_hi:[0,0,1]
	v_pk_fma_f32 v[30:31], v[86:87], v[14:15], v[34:35] op_sel_hi:[1,0,1] neg_lo:[0,0,1] neg_hi:[0,0,1]
	v_pk_fma_f32 v[34:35], v[84:85], v[14:15], v[26:27] op_sel_hi:[1,0,1] neg_lo:[0,0,1] neg_hi:[0,0,1]
	v_pk_fma_f32 v[26:27], v[90:91], v[14:15], v[32:33] op_sel_hi:[1,0,1] neg_lo:[0,0,1] neg_hi:[0,0,1]
	v_pk_fma_f32 v[32:33], v[88:89], v[14:15], v[24:25] op_sel_hi:[1,0,1] neg_lo:[0,0,1] neg_hi:[0,0,1]
; __device__ __forceinline__ unsigned cvtpk(float lo, float hi) { f32x2_t v = {lo, hi}; bf16x2_t b = __builtin_convertvector(v, bf16x2_t); return __builtin_bit_cast(unsigned, b); }
; __device__ __forceinline__ int diff_item(ldsp lds, int qt, int bh, bool pre, unsigned* nctr, const bf16* U, bf16* O, const float* subw, float lam, float omlinit, float M0, int wave, int lane) {
;     ...
;             for (int i = 0; i < 16; ++i) { const float d = o[et][i] * inv - xp[(et * 16 + i) * 64 + lane_e]; o[et][i] = d; ssq += d * d; }
;         ssq += shx(ssq, 32);
;         const float rs = omlinit / sqrtf(ssq * (1.0f / 128.0f) + EPS);
;         bf16* op = O + (tokbase + t0 + r_e) * D + h * 128 + 4 * hh_e;
;         const float* swp = subw; asm volatile("" : "+s"(swp));
; #pragma unroll
;         for (int et = 0; et < 4; ++et)
; #pragma unroll
;             for (int g4 = 0; g4 < 4; ++g4) { const int e0 = 32 * et + 8 * g4; const f32x4 w = *(const f32x4*)(swp + e0 + 4 * hh_e);
;                 v2u pk; pk.x = cvtpk(o[et][4 * g4] * rs * w[0], o[et][4 * g4 + 1] * rs * w[1]); pk.y = cvtpk(o[et][4 * g4 + 2] * rs * w[2], o[et][4 * g4 + 3] * rs * w[3]);
;                 *(v2u*)(op + e0) = pk; }
	v_pk_fma_f32 v[24:25], v[94:95], v[14:15], v[128:129] op_sel_hi:[1,0,1] neg_lo:[0,0,1] neg_hi:[0,0,1]
	v_pk_fma_f32 v[14:15], v[72:73], v[14:15], v[56:57] op_sel_hi:[1,0,1] neg_lo:[0,0,1] neg_hi:[0,0,1]
	v_add_f32_e32 v72, v146, v147
	v_add_f32_e32 v72, v72, v144
	v_add_f32_e32 v72, v72, v145
	v_add_f32_e32 v72, v72, v132
	v_pk_mul_f32 v[134:135], v[112:113], v[112:113]
	v_add_f32_e32 v72, v72, v133
	v_add_f32_e32 v72, v72, v134
	v_pk_mul_f32 v[120:121], v[118:119], v[118:119]
	v_add_f32_e32 v72, v72, v135
	v_add_f32_e32 v72, v72, v120
	v_add_f32_e32 v72, v72, v121
	v_add_f32_e32 v72, v72, v122
	v_add_f32_e32 v72, v72, v123
	v_add_f32_e32 v72, v72, v124
	v_pk_mul_f32 v[126:127], v[62:63], v[62:63]
	v_add_f32_e32 v72, v72, v125
	v_add_f32_e32 v72, v72, v126
	v_mov_b32_e32 v1, v201
	v_pk_mul_f32 v[96:97], v[60:61], v[60:61]
	v_add_f32_e32 v72, v72, v127
	v_and_or_b32 v2, v0, 31, s78
	v_mov_b32_e32 v3, s79
	v_ashrrev_i32_e32 v0, 3, v0
	v_add_f32_e32 v72, v72, v96
	v_lshlrev_b32_e32 v1, 2, v1
	v_lshlrev_b64 v[2:3], 11, v[2:3]
	v_and_b32_e32 v0, -4, v0
	v_pk_mul_f32 v[98:99], v[54:55], v[54:55]
	v_add_f32_e32 v72, v72, v97
	v_xor_b32_e32 v148, 0x80, v1
	v_lshl_add_u64 v[2:3], s[20:21], 0, v[2:3]
	v_ashrrev_i32_e32 v1, 31, v0
	v_add_f32_e32 v72, v72, v98
	v_lshl_add_u64 v[2:3], s[16:17], 1, v[2:3]
	v_pk_mul_f32 v[100:101], v[52:53], v[52:53]
	v_lshlrev_b32_e32 v12, 2, v0
	v_add_u32_e32 v12, 0x20080, v12
	v_add_f32_e32 v72, v72, v99
	v_lshl_add_u64 v[10:11], v[0:1], 1, v[2:3]
	v_and_b32_e32 v150, 32, v152
	v_lshrrev_b32_e32 v150, 2, v150
	v_mov_b32_e32 v151, 0
	v_lshl_add_u64 v[10:11], v[10:11], 0, v[150:151]
	ds_read_b128 v[0:3], v12
	v_add_f32_e32 v72, v72, v100
	v_pk_mul_f32 v[102:103], v[48:49], v[48:49]
	v_add_f32_e32 v72, v72, v101
	v_add_f32_e32 v72, v72, v102
	v_pk_mul_f32 v[104:105], v[50:51], v[50:51]
	v_add_f32_e32 v72, v72, v103
	v_add_f32_e32 v72, v72, v104
	v_pk_mul_f32 v[106:107], v[44:45], v[44:45]
	v_add_f32_e32 v72, v72, v105
	v_add_f32_e32 v72, v72, v106
	v_pk_mul_f32 v[108:109], v[46:47], v[46:47]
	v_add_f32_e32 v72, v72, v107
	v_add_f32_e32 v72, v72, v108
	v_pk_mul_f32 v[110:111], v[42:43], v[42:43]
	v_add_f32_e32 v72, v72, v109
	v_add_f32_e32 v72, v72, v110
	v_pk_mul_f32 v[80:81], v[40:41], v[40:41]
	v_add_f32_e32 v72, v72, v111
	v_add_f32_e32 v72, v72, v80
	v_pk_mul_f32 v[82:83], v[36:37], v[36:37]
	v_add_f32_e32 v72, v72, v81
	v_add_f32_e32 v72, v72, v82
	v_pk_mul_f32 v[84:85], v[34:35], v[34:35]
	v_add_f32_e32 v72, v72, v83
	v_add_f32_e32 v72, v72, v84
	v_pk_mul_f32 v[86:87], v[30:31], v[30:31]
	v_add_f32_e32 v72, v72, v85
	v_add_f32_e32 v72, v72, v86
	v_pk_mul_f32 v[88:89], v[32:33], v[32:33]
	v_add_f32_e32 v72, v72, v87
	v_add_f32_e32 v72, v72, v88
	v_pk_mul_f32 v[90:91], v[26:27], v[26:27]
	v_add_f32_e32 v72, v72, v89
	v_add_f32_e32 v72, v72, v90
	v_pk_mul_f32 v[92:93], v[28:29], v[28:29]
	v_add_f32_e32 v72, v72, v91
	v_add_f32_e32 v72, v72, v92
	v_pk_mul_f32 v[94:95], v[24:25], v[24:25]
	v_add_f32_e32 v72, v72, v93
	v_add_f32_e32 v72, v72, v94
	v_pk_mul_f32 v[64:65], v[22:23], v[22:23]
	v_add_f32_e32 v72, v72, v95
	v_add_f32_e32 v64, v72, v64
	v_pk_mul_f32 v[66:67], v[20:21], v[20:21]
	v_add_f32_e32 v64, v64, v65
	v_add_f32_e32 v64, v64, v66
	v_pk_mul_f32 v[68:69], v[18:19], v[18:19]
	v_add_f32_e32 v64, v64, v67
	v_add_f32_e32 v64, v64, v68
	v_pk_mul_f32 v[70:71], v[16:17], v[16:17]
	v_add_f32_e32 v64, v64, v69
	v_add_f32_e32 v64, v64, v70
	v_pk_mul_f32 v[56:57], v[14:15], v[14:15]
	v_add_f32_e32 v64, v64, v71
	v_add_f32_e32 v56, v64, v56
	v_pk_mul_f32 v[38:39], v[4:5], v[4:5]
	v_add_f32_e32 v56, v56, v57
	v_add_f32_e32 v38, v56, v38
	v_pk_mul_f32 v[58:59], v[6:7], v[6:7]
	v_add_f32_e32 v38, v38, v39
	v_add_f32_e32 v38, v38, v58
	v_pk_mul_f32 v[130:131], v[8:9], v[8:9]
	v_add_f32_e32 v38, v38, v59
	v_add_f32_e32 v38, v38, v130
	v_add_f32_e32 v38, v38, v131
	ds_bpermute_b32 v39, v148, v38
	s_mov_b32 s4, 0xf800000
	s_waitcnt lgkmcnt(0)
	v_add_f32_e32 v38, v38, v39
	v_fmamk_f32 v38, v38, 0x3c000000, v209
	v_cmp_gt_f32_e32 vcc, s4, v38
	v_mul_f32_e32 v39, 0x4f800000, v38
	s_nop 0
	v_cndmask_b32_e32 v38, v38, v39, vcc
	v_sqrt_f32_e32 v39, v38
	s_nop 0
	v_add_u32_e32 v56, -1, v39
	v_fma_f32 v57, -v56, v39, v38
	v_cmp_ge_f32_e64 s[16:17], 0, v57
	v_add_u32_e32 v57, 1, v39
	s_nop 0
	v_cndmask_b32_e64 v56, v39, v56, s[16:17]
	v_fma_f32 v39, -v57, v39, v38
	v_cmp_lt_f32_e64 s[16:17], 0, v39
	s_nop 1
	v_cndmask_b32_e64 v39, v56, v57, s[16:17]
	v_mul_f32_e32 v56, 0x37800000, v39
	v_cndmask_b32_e32 v39, v39, v56, vcc
	v_cmp_class_f32_e32 vcc, v38, v210
	s_nop 1
	v_cndmask_b32_e32 v38, v39, v38, vcc
	v_div_scale_f32 v39, s[4:5], v38, v38, s13
	v_rcp_f32_e32 v56, v39
	s_nop 0
	v_fma_f32 v57, -v39, v56, 1.0
	v_fmac_f32_e32 v56, v57, v56
	v_div_scale_f32 v57, vcc, s13, v38, s13
	v_mul_f32_e32 v58, v57, v56
	v_fma_f32 v59, -v39, v58, v57
	v_fmac_f32_e32 v58, v59, v56
	v_fma_f32 v39, -v39, v58, v57
	v_div_fmas_f32 v39, v39, v56, v58
	v_div_fixup_f32 v38, v39, v38, s13
	v_pk_mul_f32 v[56:57], v[114:115], v[38:39] op_sel_hi:[1,0]
	v_pk_mul_f32 v[54:55], v[54:55], v[38:39] op_sel_hi:[1,0]
	s_waitcnt lgkmcnt(0)
; __device__ __forceinline__ unsigned cvtpk(float lo, float hi) { f32x2_t v = {lo, hi}; bf16x2_t b = __builtin_convertvector(v, bf16x2_t); return __builtin_bit_cast(unsigned, b); }
; __device__ __forceinline__ int diff_item(ldsp lds, int qt, int bh, bool pre, unsigned* nctr, const bf16* U, bf16* O, const float* subw, float lam, float omlinit, float M0, int wave, int lane) {
;     ...
;         for (int et = 0; et < 4; ++et)
; #pragma unroll
;             for (int g4 = 0; g4 < 4; ++g4) { const int e0 = 32 * et + 8 * g4; const f32x4 w = *(const f32x4*)(swp + e0 + 4 * hh_e);
;                 v2u pk; pk.x = cvtpk(o[et][4 * g4] * rs * w[0], o[et][4 * g4 + 1] * rs * w[1]); pk.y = cvtpk(o[et][4 * g4 + 2] * rs * w[2], o[et][4 * g4 + 3] * rs * w[3]);
;                 *(v2u*)(op + e0) = pk; }
	v_pk_mul_f32 v[0:1], v[0:1], v[56:57]
	v_pk_mul_f32 v[56:57], v[78:79], v[38:39] op_sel_hi:[1,0]
	v_cvt_pk_bf16_f32 v0, v0, v1
	v_pk_mul_f32 v[2:3], v[2:3], v[56:57]
	v_pk_mul_f32 v[56:57], v[116:117], v[38:39] op_sel_hi:[1,0]
	v_cvt_pk_bf16_f32 v1, v2, v3
	ds_read_b128 v[192:195], v12 offset:32
	v_pk_mul_f32 v[52:53], v[52:53], v[38:39] op_sel_hi:[1,0]
	v_pk_mul_f32 v[48:49], v[48:49], v[38:39] op_sel_hi:[1,0]
	v_pk_mul_f32 v[44:45], v[44:45], v[38:39] op_sel_hi:[1,0]
	v_pk_mul_f32 v[42:43], v[42:43], v[38:39] op_sel_hi:[1,0]
	v_pk_mul_f32 v[40:41], v[40:41], v[38:39] op_sel_hi:[1,0]
	v_pk_mul_f32 v[36:37], v[36:37], v[38:39] op_sel_hi:[1,0]
	v_pk_mul_f32 v[34:35], v[34:35], v[38:39] op_sel_hi:[1,0]
	v_pk_mul_f32 v[30:31], v[30:31], v[38:39] op_sel_hi:[1,0]
	v_pk_mul_f32 v[26:27], v[26:27], v[38:39] op_sel_hi:[1,0]
	v_pk_mul_f32 v[24:25], v[24:25], v[38:39] op_sel_hi:[1,0]
	v_pk_mul_f32 v[22:23], v[22:23], v[38:39] op_sel_hi:[1,0]
	v_pk_mul_f32 v[20:21], v[20:21], v[38:39] op_sel_hi:[1,0]
	v_pk_mul_f32 v[18:19], v[18:19], v[38:39] op_sel_hi:[1,0]
	v_pk_mul_f32 v[16:17], v[16:17], v[38:39] op_sel_hi:[1,0]
	v_pk_mul_f32 v[14:15], v[14:15], v[38:39] op_sel_hi:[1,0]
	v_pk_mul_f32 v[4:5], v[4:5], v[38:39] op_sel_hi:[1,0]
	s_waitcnt lgkmcnt(0)
	v_pk_mul_f32 v[192:193], v[192:193], v[56:57]
	v_pk_mul_f32 v[56:57], v[112:113], v[38:39] op_sel_hi:[1,0]
	v_cvt_pk_bf16_f32 v2, v192, v193
	v_pk_mul_f32 v[194:195], v[194:195], v[56:57]
	v_pk_mul_f32 v[56:57], v[118:119], v[38:39] op_sel_hi:[1,0]
	v_cvt_pk_bf16_f32 v3, v194, v195
	s_nop 1
	v_permlane32_swap_b32_e32 v0, v2
	v_permlane32_swap_b32_e32 v1, v3
	global_store_dwordx4 v[10:11], v[0:3], off
	s_nop 1
	ds_read_b128 v[0:3], v12 offset:64
	s_waitcnt lgkmcnt(0)
	v_pk_mul_f32 v[0:1], v[0:1], v[56:57]
	v_pk_mul_f32 v[56:57], v[74:75], v[38:39] op_sel_hi:[1,0]
	v_cvt_pk_bf16_f32 v0, v0, v1
	v_pk_mul_f32 v[2:3], v[2:3], v[56:57]
	v_pk_mul_f32 v[56:57], v[76:77], v[38:39] op_sel_hi:[1,0]
	v_cvt_pk_bf16_f32 v1, v2, v3
	ds_read_b128 v[192:195], v12 offset:96
	s_waitcnt lgkmcnt(0)
	v_pk_mul_f32 v[192:193], v[56:57], v[192:193]
	v_pk_mul_f32 v[56:57], v[62:63], v[38:39] op_sel_hi:[1,0]
	v_cvt_pk_bf16_f32 v2, v192, v193
	v_pk_mul_f32 v[194:195], v[56:57], v[194:195]
	v_pk_mul_f32 v[56:57], v[60:61], v[38:39] op_sel_hi:[1,0]
	v_cvt_pk_bf16_f32 v3, v194, v195
	s_nop 1
	v_permlane32_swap_b32_e32 v0, v2
	v_permlane32_swap_b32_e32 v1, v3
	global_store_dwordx4 v[10:11], v[0:3], off offset:32
	s_nop 1
	ds_read_b128 v[0:3], v12 offset:128
	s_waitcnt lgkmcnt(0)
	v_pk_mul_f32 v[0:1], v[56:57], v[0:1]
	v_pk_mul_f32 v[2:3], v[54:55], v[2:3]
	v_cvt_pk_bf16_f32 v0, v0, v1
	v_cvt_pk_bf16_f32 v1, v2, v3
	ds_read_b128 v[192:195], v12 offset:160
	s_waitcnt lgkmcnt(0)
	v_pk_mul_f32 v[192:193], v[52:53], v[192:193]
	v_pk_mul_f32 v[194:195], v[48:49], v[194:195]
	v_cvt_pk_bf16_f32 v2, v192, v193
	v_cvt_pk_bf16_f32 v3, v194, v195
	s_nop 1
	v_permlane32_swap_b32_e32 v0, v2
	v_permlane32_swap_b32_e32 v1, v3
	global_store_dwordx4 v[10:11], v[0:3], off offset:64
	s_nop 1
	ds_read_b128 v[0:3], v12 offset:192
	v_pk_mul_f32 v[48:49], v[50:51], v[38:39] op_sel_hi:[1,0]
	s_waitcnt lgkmcnt(0)
	v_pk_mul_f32 v[2:3], v[44:45], v[2:3]
	v_pk_mul_f32 v[0:1], v[48:49], v[0:1]
	v_pk_mul_f32 v[44:45], v[46:47], v[38:39] op_sel_hi:[1,0]
	v_cvt_pk_bf16_f32 v0, v0, v1
	v_cvt_pk_bf16_f32 v1, v2, v3
	ds_read_b128 v[192:195], v12 offset:224
	s_waitcnt lgkmcnt(0)
	v_pk_mul_f32 v[192:193], v[44:45], v[192:193]
	v_pk_mul_f32 v[194:195], v[42:43], v[194:195]
	v_cvt_pk_bf16_f32 v2, v192, v193
	v_cvt_pk_bf16_f32 v3, v194, v195
	s_nop 1
	v_permlane32_swap_b32_e32 v0, v2
	v_permlane32_swap_b32_e32 v1, v3
	global_store_dwordx4 v[10:11], v[0:3], off offset:96
	s_nop 1
	ds_read_b128 v[0:3], v12 offset:256
	s_waitcnt lgkmcnt(0)
	v_pk_mul_f32 v[0:1], v[40:41], v[0:1]
	v_pk_mul_f32 v[2:3], v[36:37], v[2:3]
	v_cvt_pk_bf16_f32 v0, v0, v1
	v_cvt_pk_bf16_f32 v1, v2, v3
	ds_read_b128 v[192:195], v12 offset:288
	s_waitcnt lgkmcnt(0)
	v_pk_mul_f32 v[192:193], v[34:35], v[192:193]
	v_pk_mul_f32 v[194:195], v[30:31], v[194:195]
	v_cvt_pk_bf16_f32 v2, v192, v193
	v_cvt_pk_bf16_f32 v3, v194, v195
	s_nop 1
	v_permlane32_swap_b32_e32 v0, v2
	v_permlane32_swap_b32_e32 v1, v3
	global_store_dwordx4 v[10:11], v[0:3], off offset:128
	s_nop 1
	ds_read_b128 v[0:3], v12 offset:320
	v_pk_mul_f32 v[30:31], v[32:33], v[38:39] op_sel_hi:[1,0]
	s_waitcnt lgkmcnt(0)
	v_pk_mul_f32 v[2:3], v[26:27], v[2:3]
	v_pk_mul_f32 v[0:1], v[30:31], v[0:1]
	v_pk_mul_f32 v[26:27], v[28:29], v[38:39] op_sel_hi:[1,0]
	v_cvt_pk_bf16_f32 v0, v0, v1
	v_cvt_pk_bf16_f32 v1, v2, v3
	ds_read_b128 v[192:195], v12 offset:352
	s_waitcnt lgkmcnt(0)
	v_pk_mul_f32 v[192:193], v[26:27], v[192:193]
	v_pk_mul_f32 v[194:195], v[24:25], v[194:195]
	v_cvt_pk_bf16_f32 v2, v192, v193
	v_cvt_pk_bf16_f32 v3, v194, v195
	s_nop 1
	v_permlane32_swap_b32_e32 v0, v2
	v_permlane32_swap_b32_e32 v1, v3
	global_store_dwordx4 v[10:11], v[0:3], off offset:160
	s_nop 1
	ds_read_b128 v[0:3], v12 offset:384
	s_waitcnt lgkmcnt(0)
	v_pk_mul_f32 v[0:1], v[22:23], v[0:1]
	v_pk_mul_f32 v[2:3], v[20:21], v[2:3]
	v_cvt_pk_bf16_f32 v0, v0, v1
	v_cvt_pk_bf16_f32 v1, v2, v3
	ds_read_b128 v[192:195], v12 offset:416
	s_waitcnt lgkmcnt(0)
	v_pk_mul_f32 v[192:193], v[18:19], v[192:193]
	v_pk_mul_f32 v[194:195], v[16:17], v[194:195]
	v_cvt_pk_bf16_f32 v2, v192, v193
	v_cvt_pk_bf16_f32 v3, v194, v195
	s_nop 1
	v_permlane32_swap_b32_e32 v0, v2
	v_permlane32_swap_b32_e32 v1, v3
	global_store_dwordx4 v[10:11], v[0:3], off offset:192
	s_nop 1
	ds_read_b128 v[0:3], v12 offset:448
	s_waitcnt lgkmcnt(0)
	v_pk_mul_f32 v[0:1], v[14:15], v[0:1]
	v_pk_mul_f32 v[2:3], v[4:5], v[2:3]
	v_cvt_pk_bf16_f32 v0, v0, v1
	v_cvt_pk_bf16_f32 v1, v2, v3
	ds_read_b128 v[192:195], v12 offset:480
	v_pk_mul_f32 v[4:5], v[6:7], v[38:39] op_sel_hi:[1,0]
	s_waitcnt lgkmcnt(0)
	v_pk_mul_f32 v[192:193], v[4:5], v[192:193]
	v_pk_mul_f32 v[4:5], v[8:9], v[38:39] op_sel_hi:[1,0]
	v_cvt_pk_bf16_f32 v2, v192, v193
	v_pk_mul_f32 v[194:195], v[4:5], v[194:195]
	s_nop 0
	v_cvt_pk_bf16_f32 v3, v194, v195
	s_nop 1
	v_permlane32_swap_b32_e32 v0, v2
	v_permlane32_swap_b32_e32 v1, v3
	global_store_dwordx4 v[10:11], v[0:3], off offset:224
	s_nop 1
	s_branch .LBB0_1848
